# GEMM mainloops (GEMM1/P4/P5 main/P6): one s_setprio 1 at the top of the compute body and one s_setprio 0 at its end, instead of a flip around every MFMA cluster
# speedup vs baseline: 1.0148x; 1.0046x over previous
; template <int MI>
; DEV void gemm_mm(f32x16 (&acc)[MI][2], const u16* __restrict__ A, int lda, const u16* __restrict__ B, int ldb, int K,
;                  unsigned char* smem) {
;     ...
;     bf16x8 af[2][MI], bfr[2][2];
; #pragma unroll
;     for (int i = 0; i < MI; ++i) af[0][i] = *(const bf16x8*)(sA + (wm * (MI * 32) + i * 32) * LDT + fro);
; #pragma unroll
;     for (int i = 0; i < 2; ++i) bfr[0][i] = *(const bf16x8*)(sB + (wn * 64 + i * 32) * LDT + fro);
; #pragma unroll
;     for (int ks = 0; ks < 4; ++ks) {
;       if (ks + 1 < 4) {
; #pragma unroll
;         for (int i = 0; i < MI; ++i)
;           af[(ks + 1) & 1][i] = *(const bf16x8*)(sA + (wm * (MI * 32) + i * 32) * LDT + fro + (ks + 1) * 16);
; #pragma unroll
;         for (int i = 0; i < 2; ++i)
;           bfr[(ks + 1) & 1][i] = *(const bf16x8*)(sB + (wn * 64 + i * 32) * LDT + fro + (ks + 1) * 16);
;       }
;       __builtin_amdgcn_sched_barrier(0);
;       __builtin_amdgcn_s_setprio(1);
; #pragma unroll
;       for (int mi = 0; mi < MI; ++mi)
; #pragma unroll
;         for (int ni = 0; ni < 2; ++ni)
;           acc[mi][ni] = __builtin_amdgcn_mfma_f32_32x32x16_bf16(af[ks & 1][mi], bfr[ks & 1][ni], acc[mi][ni], 0, 0, 0);
;       __builtin_amdgcn_s_setprio(0);
;       __builtin_amdgcn_sched_barrier(0);
;     }
.LBB0_282:
	s_setprio 1
	ds_read_b128 v[184:187], v181
	ds_read_b128 v[188:191], v181 offset:32
	ds_read_b128 v[192:195], v181 offset:4608
	ds_read_b128 v[196:199], v181 offset:4640
	ds_read_b128 v[200:203], v181 offset:9216
	ds_read_b128 v[204:207], v181 offset:9248
	ds_read_b128 v[208:211], v181 offset:13824
	ds_read_b128 v[212:215], v181 offset:13856
	ds_read_b128 v[216:219], v182 offset:36864
	ds_read_b128 v[220:223], v182 offset:36896
	ds_read_b128 v[226:229], v182 offset:41472
	ds_read_b128 v[248:251], v182 offset:41504
	s_waitcnt lgkmcnt(3)
	v_mfma_f32_32x32x16_bf16 v[112:127], v[184:187], v[216:219], v[112:127]
	s_waitcnt lgkmcnt(1)
	v_mfma_f32_32x32x16_bf16 v[96:111], v[184:187], v[226:229], v[96:111]
	v_mfma_f32_32x32x16_bf16 v[80:95], v[192:195], v[216:219], v[80:95]
	v_mfma_f32_32x32x16_bf16 v[64:79], v[192:195], v[226:229], v[64:79]
	v_mfma_f32_32x32x16_bf16 v[48:63], v[200:203], v[216:219], v[48:63]
	v_mfma_f32_32x32x16_bf16 v[32:47], v[200:203], v[226:229], v[32:47]
	v_mfma_f32_32x32x16_bf16 v[16:31], v[208:211], v[216:219], v[16:31]
	v_mfma_f32_32x32x16_bf16 v[0:15], v[208:211], v[226:229], v[0:15]
	ds_read_b128 v[184:187], v181 offset:64
	ds_read_b128 v[192:195], v181 offset:4672
	ds_read_b128 v[200:203], v181 offset:9280
	ds_read_b128 v[208:211], v181 offset:13888
	ds_read_b128 v[216:219], v182 offset:36928
	ds_read_b128 v[226:229], v182 offset:41536
	v_mfma_f32_32x32x16_bf16 v[112:127], v[188:191], v[220:223], v[112:127]
	s_waitcnt lgkmcnt(6)
	v_mfma_f32_32x32x16_bf16 v[96:111], v[188:191], v[248:251], v[96:111]
	v_mfma_f32_32x32x16_bf16 v[80:95], v[196:199], v[220:223], v[80:95]
	v_mfma_f32_32x32x16_bf16 v[64:79], v[196:199], v[248:251], v[64:79]
	v_mfma_f32_32x32x16_bf16 v[48:63], v[204:207], v[220:223], v[48:63]
	v_mfma_f32_32x32x16_bf16 v[32:47], v[204:207], v[248:251], v[32:47]
	v_mfma_f32_32x32x16_bf16 v[16:31], v[212:215], v[220:223], v[16:31]
	v_mfma_f32_32x32x16_bf16 v[0:15], v[212:215], v[248:251], v[0:15]
	ds_read_b128 v[188:191], v181 offset:96
	ds_read_b128 v[196:199], v181 offset:4704
	ds_read_b128 v[204:207], v181 offset:9312
	ds_read_b128 v[212:215], v181 offset:13920
	ds_read_b128 v[220:223], v182 offset:36960
	ds_read_b128 v[248:251], v182 offset:41568
	s_waitcnt lgkmcnt(7)
	v_mfma_f32_32x32x16_bf16 v[112:127], v[184:187], v[216:219], v[112:127]
	s_waitcnt lgkmcnt(6)
	v_mfma_f32_32x32x16_bf16 v[96:111], v[184:187], v[226:229], v[96:111]
	v_mfma_f32_32x32x16_bf16 v[80:95], v[192:195], v[216:219], v[80:95]
	v_mfma_f32_32x32x16_bf16 v[64:79], v[192:195], v[226:229], v[64:79]
	v_mfma_f32_32x32x16_bf16 v[48:63], v[200:203], v[216:219], v[48:63]
	v_mfma_f32_32x32x16_bf16 v[32:47], v[200:203], v[226:229], v[32:47]
	v_mfma_f32_32x32x16_bf16 v[16:31], v[208:211], v[216:219], v[16:31]
	v_mfma_f32_32x32x16_bf16 v[0:15], v[208:211], v[226:229], v[0:15]
	s_waitcnt lgkmcnt(1)
	v_mfma_f32_32x32x16_bf16 v[112:127], v[188:191], v[220:223], v[112:127]
	s_waitcnt lgkmcnt(0)
	v_mfma_f32_32x32x16_bf16 v[96:111], v[188:191], v[248:251], v[96:111]
	v_mfma_f32_32x32x16_bf16 v[80:95], v[196:199], v[220:223], v[80:95]
	v_mfma_f32_32x32x16_bf16 v[64:79], v[196:199], v[248:251], v[64:79]
	v_mfma_f32_32x32x16_bf16 v[48:63], v[204:207], v[220:223], v[48:63]
	v_mfma_f32_32x32x16_bf16 v[32:47], v[204:207], v[248:251], v[32:47]
	v_mfma_f32_32x32x16_bf16 v[16:31], v[212:215], v[220:223], v[16:31]
	v_mfma_f32_32x32x16_bf16 v[0:15], v[212:215], v[248:251], v[0:15]
	s_setprio 0
	s_add_i32 s1, s1, -1
	s_cmp_lg_u32 s1, 0
	s_cbranch_scc0 .LBB0_285

; template <int MI>
; DEV void gemm_mm(f32x16 (&acc)[MI][2], const u16* __restrict__ A, int lda, const u16* __restrict__ B, int ldb, int K,
;                  unsigned char* smem) {
;     ...
;     bf16x8 af[2][MI], bfr[2][2];
; #pragma unroll
;     for (int i = 0; i < MI; ++i) af[0][i] = *(const bf16x8*)(sA + (wm * (MI * 32) + i * 32) * LDT + fro);
; #pragma unroll
;     for (int i = 0; i < 2; ++i) bfr[0][i] = *(const bf16x8*)(sB + (wn * 64 + i * 32) * LDT + fro);
; #pragma unroll
;     for (int ks = 0; ks < 4; ++ks) {
;       if (ks + 1 < 4) {
; #pragma unroll
;         for (int i = 0; i < MI; ++i)
;           af[(ks + 1) & 1][i] = *(const bf16x8*)(sA + (wm * (MI * 32) + i * 32) * LDT + fro + (ks + 1) * 16);
; #pragma unroll
;         for (int i = 0; i < 2; ++i)
;           bfr[(ks + 1) & 1][i] = *(const bf16x8*)(sB + (wn * 64 + i * 32) * LDT + fro + (ks + 1) * 16);
;       }
;       __builtin_amdgcn_sched_barrier(0);
;       __builtin_amdgcn_s_setprio(1);
; #pragma unroll
;       for (int mi = 0; mi < MI; ++mi)
; #pragma unroll
;         for (int ni = 0; ni < 2; ++ni)
;           acc[mi][ni] = __builtin_amdgcn_mfma_f32_32x32x16_bf16(af[ks & 1][mi], bfr[ks & 1][ni], acc[mi][ni], 0, 0, 0);
;       __builtin_amdgcn_s_setprio(0);
;       __builtin_amdgcn_sched_barrier(0);
;     }
.LBB0_449:
	s_setprio 1
	ds_read_b128 v[104:107], v101
	ds_read_b128 v[108:111], v101 offset:32
	ds_read_b128 v[112:115], v101 offset:4608
	ds_read_b128 v[116:119], v101 offset:4640
	ds_read_b128 v[120:123], v102 offset:18432
	ds_read_b128 v[124:127], v102 offset:18464
	ds_read_b128 v[128:131], v102 offset:23040
	ds_read_b128 v[132:135], v102 offset:23072
	s_add_i32 s1, s1, 1
	s_waitcnt lgkmcnt(3)
	v_mfma_f32_32x32x16_bf16 v[48:63], v[104:107], v[120:123], v[48:63]
	s_waitcnt lgkmcnt(1)
	v_mfma_f32_32x32x16_bf16 v[32:47], v[104:107], v[128:131], v[32:47]
	v_mfma_f32_32x32x16_bf16 v[16:31], v[112:115], v[120:123], v[16:31]
	v_mfma_f32_32x32x16_bf16 v[0:15], v[112:115], v[128:131], v[0:15]
	ds_read_b128 v[104:107], v101 offset:64
	ds_read_b128 v[112:115], v101 offset:4672
	ds_read_b128 v[120:123], v102 offset:18496
	ds_read_b128 v[128:131], v102 offset:23104
	v_mfma_f32_32x32x16_bf16 v[48:63], v[108:111], v[124:127], v[48:63]
	s_waitcnt lgkmcnt(4)
	v_mfma_f32_32x32x16_bf16 v[32:47], v[108:111], v[132:135], v[32:47]
	v_mfma_f32_32x32x16_bf16 v[16:31], v[116:119], v[124:127], v[16:31]
	v_mfma_f32_32x32x16_bf16 v[0:15], v[116:119], v[132:135], v[0:15]
	ds_read_b128 v[108:111], v101 offset:96
	ds_read_b128 v[116:119], v101 offset:4704
	ds_read_b128 v[124:127], v102 offset:18528
	ds_read_b128 v[132:135], v102 offset:23136
	s_waitcnt lgkmcnt(5)
	v_mfma_f32_32x32x16_bf16 v[48:63], v[104:107], v[120:123], v[48:63]
	s_waitcnt lgkmcnt(4)
	v_mfma_f32_32x32x16_bf16 v[32:47], v[104:107], v[128:131], v[32:47]
	v_mfma_f32_32x32x16_bf16 v[16:31], v[112:115], v[120:123], v[16:31]
	v_mfma_f32_32x32x16_bf16 v[0:15], v[112:115], v[128:131], v[0:15]
	s_waitcnt lgkmcnt(1)
	v_mfma_f32_32x32x16_bf16 v[48:63], v[108:111], v[124:127], v[48:63]
	s_waitcnt lgkmcnt(0)
	v_mfma_f32_32x32x16_bf16 v[32:47], v[108:111], v[132:135], v[32:47]
	v_mfma_f32_32x32x16_bf16 v[16:31], v[116:119], v[124:127], v[16:31]
	v_mfma_f32_32x32x16_bf16 v[0:15], v[116:119], v[132:135], v[0:15]
	s_setprio 0
	s_cmp_lg_u32 s1, 16
	s_cbranch_scc0 .LBB0_452

; template <int MI>
; DEV void gemm_mm(f32x16 (&acc)[MI][2], const u16* __restrict__ A, int lda, const u16* __restrict__ B, int ldb, int K,
;                  unsigned char* smem) {
;     ...
;     bf16x8 af[2][MI], bfr[2][2];
; #pragma unroll
;     for (int i = 0; i < MI; ++i) af[0][i] = *(const bf16x8*)(sA + (wm * (MI * 32) + i * 32) * LDT + fro);
; #pragma unroll
;     for (int i = 0; i < 2; ++i) bfr[0][i] = *(const bf16x8*)(sB + (wn * 64 + i * 32) * LDT + fro);
; #pragma unroll
;     for (int ks = 0; ks < 4; ++ks) {
;       if (ks + 1 < 4) {
; #pragma unroll
;         for (int i = 0; i < MI; ++i)
;           af[(ks + 1) & 1][i] = *(const bf16x8*)(sA + (wm * (MI * 32) + i * 32) * LDT + fro + (ks + 1) * 16);
; #pragma unroll
;         for (int i = 0; i < 2; ++i)
;           bfr[(ks + 1) & 1][i] = *(const bf16x8*)(sB + (wn * 64 + i * 32) * LDT + fro + (ks + 1) * 16);
;       }
;       __builtin_amdgcn_sched_barrier(0);
;       __builtin_amdgcn_s_setprio(1);
; #pragma unroll
;       for (int mi = 0; mi < MI; ++mi)
; #pragma unroll
;         for (int ni = 0; ni < 2; ++ni)
;           acc[mi][ni] = __builtin_amdgcn_mfma_f32_32x32x16_bf16(af[ks & 1][mi], bfr[ks & 1][ni], acc[mi][ni], 0, 0, 0);
;       __builtin_amdgcn_s_setprio(0);
;       __builtin_amdgcn_sched_barrier(0);
;     }
.LBB0_1215:
	s_setprio 1
	ds_read_b128 v[184:187], v181
	ds_read_b128 v[188:191], v181 offset:32
	ds_read_b128 v[192:195], v181 offset:4608
	ds_read_b128 v[196:199], v181 offset:4640
	ds_read_b128 v[200:203], v181 offset:9216
	ds_read_b128 v[204:207], v181 offset:9248
	ds_read_b128 v[208:211], v181 offset:13824
	ds_read_b128 v[212:215], v181 offset:13856
	ds_read_b128 v[216:219], v182 offset:36864
	ds_read_b128 v[220:223], v182 offset:36896
	ds_read_b128 v[226:229], v182 offset:41472
	ds_read_b128 v[234:237], v182 offset:41504
	s_waitcnt lgkmcnt(3)
	v_mfma_f32_32x32x16_bf16 v[112:127], v[184:187], v[216:219], v[112:127]
	s_waitcnt lgkmcnt(1)
	v_mfma_f32_32x32x16_bf16 v[96:111], v[184:187], v[226:229], v[96:111]
	v_mfma_f32_32x32x16_bf16 v[80:95], v[192:195], v[216:219], v[80:95]
	v_mfma_f32_32x32x16_bf16 v[64:79], v[192:195], v[226:229], v[64:79]
	v_mfma_f32_32x32x16_bf16 v[48:63], v[200:203], v[216:219], v[48:63]
	v_mfma_f32_32x32x16_bf16 v[32:47], v[200:203], v[226:229], v[32:47]
	v_mfma_f32_32x32x16_bf16 v[16:31], v[208:211], v[216:219], v[16:31]
	v_mfma_f32_32x32x16_bf16 v[0:15], v[208:211], v[226:229], v[0:15]
	ds_read_b128 v[184:187], v181 offset:64
	ds_read_b128 v[192:195], v181 offset:4672
	ds_read_b128 v[200:203], v181 offset:9280
	ds_read_b128 v[208:211], v181 offset:13888
	ds_read_b128 v[216:219], v182 offset:36928
	ds_read_b128 v[226:229], v182 offset:41536
	v_mfma_f32_32x32x16_bf16 v[112:127], v[188:191], v[220:223], v[112:127]
	s_waitcnt lgkmcnt(6)
	v_mfma_f32_32x32x16_bf16 v[96:111], v[188:191], v[234:237], v[96:111]
	v_mfma_f32_32x32x16_bf16 v[80:95], v[196:199], v[220:223], v[80:95]
	v_mfma_f32_32x32x16_bf16 v[64:79], v[196:199], v[234:237], v[64:79]
	v_mfma_f32_32x32x16_bf16 v[48:63], v[204:207], v[220:223], v[48:63]
	v_mfma_f32_32x32x16_bf16 v[32:47], v[204:207], v[234:237], v[32:47]
	v_mfma_f32_32x32x16_bf16 v[16:31], v[212:215], v[220:223], v[16:31]
	v_mfma_f32_32x32x16_bf16 v[0:15], v[212:215], v[234:237], v[0:15]
	ds_read_b128 v[188:191], v181 offset:96
	ds_read_b128 v[196:199], v181 offset:4704
	ds_read_b128 v[204:207], v181 offset:9312
	ds_read_b128 v[212:215], v181 offset:13920
	ds_read_b128 v[220:223], v182 offset:36960
	ds_read_b128 v[234:237], v182 offset:41568
	s_waitcnt lgkmcnt(7)
	v_mfma_f32_32x32x16_bf16 v[112:127], v[184:187], v[216:219], v[112:127]
	s_waitcnt lgkmcnt(6)
	v_mfma_f32_32x32x16_bf16 v[96:111], v[184:187], v[226:229], v[96:111]
	v_mfma_f32_32x32x16_bf16 v[80:95], v[192:195], v[216:219], v[80:95]
	v_mfma_f32_32x32x16_bf16 v[64:79], v[192:195], v[226:229], v[64:79]
	v_mfma_f32_32x32x16_bf16 v[48:63], v[200:203], v[216:219], v[48:63]
	v_mfma_f32_32x32x16_bf16 v[32:47], v[200:203], v[226:229], v[32:47]
	v_mfma_f32_32x32x16_bf16 v[16:31], v[208:211], v[216:219], v[16:31]
	v_mfma_f32_32x32x16_bf16 v[0:15], v[208:211], v[226:229], v[0:15]
	s_waitcnt lgkmcnt(1)
	v_mfma_f32_32x32x16_bf16 v[112:127], v[188:191], v[220:223], v[112:127]
	s_waitcnt lgkmcnt(0)
	v_mfma_f32_32x32x16_bf16 v[96:111], v[188:191], v[234:237], v[96:111]
	v_mfma_f32_32x32x16_bf16 v[80:95], v[196:199], v[220:223], v[80:95]
	v_mfma_f32_32x32x16_bf16 v[64:79], v[196:199], v[234:237], v[64:79]
	v_mfma_f32_32x32x16_bf16 v[48:63], v[204:207], v[220:223], v[48:63]
	v_mfma_f32_32x32x16_bf16 v[32:47], v[204:207], v[234:237], v[32:47]
	v_mfma_f32_32x32x16_bf16 v[16:31], v[212:215], v[220:223], v[16:31]
	v_mfma_f32_32x32x16_bf16 v[0:15], v[212:215], v[234:237], v[0:15]
	s_setprio 0
	s_add_i32 s1, s1, -1
	s_cmp_lg_u32 s1, 0
	s_cbranch_scc0 .LBB0_1218

; template <int MI>
; DEV void gemm_mm(f32x16 (&acc)[MI][2], const u16* __restrict__ A, int lda, const u16* __restrict__ B, int ldb, int K,
;                  unsigned char* smem) {
;     ...
;     bf16x8 af[2][MI], bfr[2][2];
; #pragma unroll
;     for (int i = 0; i < MI; ++i) af[0][i] = *(const bf16x8*)(sA + (wm * (MI * 32) + i * 32) * LDT + fro);
; #pragma unroll
;     for (int i = 0; i < 2; ++i) bfr[0][i] = *(const bf16x8*)(sB + (wn * 64 + i * 32) * LDT + fro);
; #pragma unroll
;     for (int ks = 0; ks < 4; ++ks) {
;       if (ks + 1 < 4) {
; #pragma unroll
;         for (int i = 0; i < MI; ++i)
;           af[(ks + 1) & 1][i] = *(const bf16x8*)(sA + (wm * (MI * 32) + i * 32) * LDT + fro + (ks + 1) * 16);
; #pragma unroll
;         for (int i = 0; i < 2; ++i)
;           bfr[(ks + 1) & 1][i] = *(const bf16x8*)(sB + (wn * 64 + i * 32) * LDT + fro + (ks + 1) * 16);
;       }
;       __builtin_amdgcn_sched_barrier(0);
;       __builtin_amdgcn_s_setprio(1);
; #pragma unroll
;       for (int mi = 0; mi < MI; ++mi)
; #pragma unroll
;         for (int ni = 0; ni < 2; ++ni)
;           acc[mi][ni] = __builtin_amdgcn_mfma_f32_32x32x16_bf16(af[ks & 1][mi], bfr[ks & 1][ni], acc[mi][ni], 0, 0, 0);
;       __builtin_amdgcn_s_setprio(0);
;       __builtin_amdgcn_sched_barrier(0);
;     }
.LBB0_1243:
	s_setprio 1
	ds_read_b128 v[104:107], v101
	ds_read_b128 v[108:111], v101 offset:32
	ds_read_b128 v[112:115], v101 offset:4608
	ds_read_b128 v[116:119], v101 offset:4640
	ds_read_b128 v[120:123], v102 offset:18432
	ds_read_b128 v[124:127], v102 offset:18464
	ds_read_b128 v[128:131], v102 offset:23040
	ds_read_b128 v[132:135], v102 offset:23072
	s_add_i32 s1, s1, 1
	s_waitcnt lgkmcnt(3)
	v_mfma_f32_32x32x16_bf16 v[64:79], v[104:107], v[120:123], v[64:79]
	s_waitcnt lgkmcnt(1)
	v_mfma_f32_32x32x16_bf16 v[32:47], v[104:107], v[128:131], v[32:47]
	v_mfma_f32_32x32x16_bf16 v[16:31], v[112:115], v[120:123], v[16:31]
	v_mfma_f32_32x32x16_bf16 v[0:15], v[112:115], v[128:131], v[0:15]
	ds_read_b128 v[104:107], v101 offset:64
	ds_read_b128 v[112:115], v101 offset:4672
	ds_read_b128 v[120:123], v102 offset:18496
	ds_read_b128 v[128:131], v102 offset:23104
	v_mfma_f32_32x32x16_bf16 v[64:79], v[108:111], v[124:127], v[64:79]
	s_waitcnt lgkmcnt(4)
	v_mfma_f32_32x32x16_bf16 v[32:47], v[108:111], v[132:135], v[32:47]
	v_mfma_f32_32x32x16_bf16 v[16:31], v[116:119], v[124:127], v[16:31]
	v_mfma_f32_32x32x16_bf16 v[0:15], v[116:119], v[132:135], v[0:15]
	ds_read_b128 v[108:111], v101 offset:96
	ds_read_b128 v[116:119], v101 offset:4704
	ds_read_b128 v[124:127], v102 offset:18528
	ds_read_b128 v[132:135], v102 offset:23136
	s_waitcnt lgkmcnt(5)
	v_mfma_f32_32x32x16_bf16 v[64:79], v[104:107], v[120:123], v[64:79]
	s_waitcnt lgkmcnt(4)
	v_mfma_f32_32x32x16_bf16 v[32:47], v[104:107], v[128:131], v[32:47]
	v_mfma_f32_32x32x16_bf16 v[16:31], v[112:115], v[120:123], v[16:31]
	v_mfma_f32_32x32x16_bf16 v[0:15], v[112:115], v[128:131], v[0:15]
	s_waitcnt lgkmcnt(1)
	v_mfma_f32_32x32x16_bf16 v[64:79], v[108:111], v[124:127], v[64:79]
	s_waitcnt lgkmcnt(0)
	v_mfma_f32_32x32x16_bf16 v[32:47], v[108:111], v[132:135], v[32:47]
	v_mfma_f32_32x32x16_bf16 v[16:31], v[116:119], v[124:127], v[16:31]
	v_mfma_f32_32x32x16_bf16 v[0:15], v[116:119], v[132:135], v[0:15]
	s_setprio 0
	s_cmp_lg_u32 s1, 4
	s_cbranch_scc0 .LBB0_1246

; template <int MI>
; DEV void gemm_mm(f32x16 (&acc)[MI][2], const u16* __restrict__ A, int lda, const u16* __restrict__ B, int ldb, int K,
;                  unsigned char* smem) {
;     ...
;     bf16x8 af[2][MI], bfr[2][2];
; #pragma unroll
;     for (int i = 0; i < MI; ++i) af[0][i] = *(const bf16x8*)(sA + (wm * (MI * 32) + i * 32) * LDT + fro);
; #pragma unroll
;     for (int i = 0; i < 2; ++i) bfr[0][i] = *(const bf16x8*)(sB + (wn * 64 + i * 32) * LDT + fro);
; #pragma unroll
;     for (int ks = 0; ks < 4; ++ks) {
;       if (ks + 1 < 4) {
; #pragma unroll
;         for (int i = 0; i < MI; ++i)
;           af[(ks + 1) & 1][i] = *(const bf16x8*)(sA + (wm * (MI * 32) + i * 32) * LDT + fro + (ks + 1) * 16);
; #pragma unroll
;         for (int i = 0; i < 2; ++i)
;           bfr[(ks + 1) & 1][i] = *(const bf16x8*)(sB + (wn * 64 + i * 32) * LDT + fro + (ks + 1) * 16);
;       }
;       __builtin_amdgcn_sched_barrier(0);
;       __builtin_amdgcn_s_setprio(1);
; #pragma unroll
;       for (int mi = 0; mi < MI; ++mi)
; #pragma unroll
;         for (int ni = 0; ni < 2; ++ni)
;           acc[mi][ni] = __builtin_amdgcn_mfma_f32_32x32x16_bf16(af[ks & 1][mi], bfr[ks & 1][ni], acc[mi][ni], 0, 0, 0);
;       __builtin_amdgcn_s_setprio(0);
;       __builtin_amdgcn_sched_barrier(0);
;     }
.LBB0_1247:
	s_setprio 1
	ds_read_b128 v[168:171], v165
	ds_read_b128 v[172:175], v165 offset:32
	ds_read_b128 v[176:179], v165 offset:4608
	ds_read_b128 v[180:183], v165 offset:4640
	ds_read_b128 v[184:187], v166 offset:18432
	ds_read_b128 v[188:191], v166 offset:18464
	ds_read_b128 v[192:195], v166 offset:23040
	ds_read_b128 v[196:199], v166 offset:23072
	s_add_i32 s0, s0, 1
	s_waitcnt lgkmcnt(3)
	v_mfma_f32_32x32x16_bf16 v[112:127], v[168:171], v[184:187], v[112:127]
	s_waitcnt lgkmcnt(1)
	v_mfma_f32_32x32x16_bf16 v[96:111], v[168:171], v[192:195], v[96:111]
	v_mfma_f32_32x32x16_bf16 v[80:95], v[176:179], v[184:187], v[80:95]
	v_mfma_f32_32x32x16_bf16 v[48:63], v[176:179], v[192:195], v[48:63]
	ds_read_b128 v[168:171], v165 offset:64
	ds_read_b128 v[176:179], v165 offset:4672
	ds_read_b128 v[184:187], v166 offset:18496
	ds_read_b128 v[192:195], v166 offset:23104
	v_mfma_f32_32x32x16_bf16 v[112:127], v[172:175], v[188:191], v[112:127]
	s_waitcnt lgkmcnt(4)
	v_mfma_f32_32x32x16_bf16 v[96:111], v[172:175], v[196:199], v[96:111]
	v_mfma_f32_32x32x16_bf16 v[80:95], v[180:183], v[188:191], v[80:95]
	v_mfma_f32_32x32x16_bf16 v[48:63], v[180:183], v[196:199], v[48:63]
	ds_read_b128 v[172:175], v165 offset:96
	ds_read_b128 v[180:183], v165 offset:4704
	ds_read_b128 v[188:191], v166 offset:18528
	ds_read_b128 v[196:199], v166 offset:23136
	s_waitcnt lgkmcnt(5)
	v_mfma_f32_32x32x16_bf16 v[112:127], v[168:171], v[184:187], v[112:127]
	s_waitcnt lgkmcnt(4)
	v_mfma_f32_32x32x16_bf16 v[96:111], v[168:171], v[192:195], v[96:111]
	v_mfma_f32_32x32x16_bf16 v[80:95], v[176:179], v[184:187], v[80:95]
	v_mfma_f32_32x32x16_bf16 v[48:63], v[176:179], v[192:195], v[48:63]
	s_waitcnt lgkmcnt(1)
	v_mfma_f32_32x32x16_bf16 v[112:127], v[172:175], v[188:191], v[112:127]
	s_waitcnt lgkmcnt(0)
	v_mfma_f32_32x32x16_bf16 v[96:111], v[172:175], v[196:199], v[96:111]
	v_mfma_f32_32x32x16_bf16 v[80:95], v[180:183], v[188:191], v[80:95]
	v_mfma_f32_32x32x16_bf16 v[48:63], v[180:183], v[196:199], v[48:63]
	s_setprio 0
	s_cmp_lg_u32 s0, 16
	s_cbranch_scc0 .LBB0_1226

;     ...
; #pragma unroll
;       for (int ks = 0; ks < 4; ++ks) {
;         bf16x8 af[2], bfr[2];
; #pragma unroll
;         for (int i = 0; i < 2; ++i) {
;           af[i] = *(const bf16x8*)(sA + (wm * 64 + i * 32) * LDT + fro + ks * 16);
;           bfr[i] = *(const bf16x8*)(sB + (wn * 64 + i * 32) * LDT + fro + ks * 16);
;         }
;         __builtin_amdgcn_s_setprio(1);
; #pragma unroll
;         for (int mi = 0; mi < 2; ++mi)
; #pragma unroll
;           for (int ni = 0; ni < 2; ++ni)
;             acc[mi][ni] = __builtin_amdgcn_mfma_f32_32x32x16_bf16(af[mi], bfr[ni], acc[mi][ni], 0, 0, 0);
;         __builtin_amdgcn_s_setprio(0);
;       }
.LBB0_1312:
	s_setprio 1
	ds_read_b128 v[168:171], v165
	ds_read_b128 v[172:175], v165 offset:4608
	ds_read_b128 v[176:179], v166 offset:18432
	ds_read_b128 v[180:183], v166 offset:23040
	s_waitcnt lgkmcnt(1)
	v_mfma_f32_32x32x16_bf16 v[144:159], v[168:171], v[176:179], v[144:159]
	s_waitcnt lgkmcnt(0)
	v_mfma_f32_32x32x16_bf16 v[128:143], v[168:171], v[180:183], v[128:143]
	v_mfma_f32_32x32x16_bf16 v[112:127], v[172:175], v[176:179], v[112:127]
	v_mfma_f32_32x32x16_bf16 v[80:95], v[172:175], v[180:183], v[80:95]
	ds_read_b128 v[168:171], v165 offset:32
	ds_read_b128 v[172:175], v165 offset:4640
	ds_read_b128 v[176:179], v166 offset:18464
	ds_read_b128 v[180:183], v166 offset:23072
	s_waitcnt lgkmcnt(1)
	v_mfma_f32_32x32x16_bf16 v[144:159], v[168:171], v[176:179], v[144:159]
	s_waitcnt lgkmcnt(0)
	v_mfma_f32_32x32x16_bf16 v[128:143], v[168:171], v[180:183], v[128:143]
	v_mfma_f32_32x32x16_bf16 v[112:127], v[172:175], v[176:179], v[112:127]
	v_mfma_f32_32x32x16_bf16 v[80:95], v[172:175], v[180:183], v[80:95]
	ds_read_b128 v[168:171], v165 offset:64
	ds_read_b128 v[172:175], v165 offset:4672
	ds_read_b128 v[176:179], v166 offset:18496
	ds_read_b128 v[180:183], v166 offset:23104
	s_waitcnt lgkmcnt(1)
	v_mfma_f32_32x32x16_bf16 v[144:159], v[168:171], v[176:179], v[144:159]
	s_waitcnt lgkmcnt(0)
	v_mfma_f32_32x32x16_bf16 v[128:143], v[168:171], v[180:183], v[128:143]
	v_mfma_f32_32x32x16_bf16 v[112:127], v[172:175], v[176:179], v[112:127]
	v_mfma_f32_32x32x16_bf16 v[80:95], v[172:175], v[180:183], v[80:95]
	ds_read_b128 v[168:171], v165 offset:96
	ds_read_b128 v[172:175], v165 offset:4704
	ds_read_b128 v[176:179], v166 offset:18528
	ds_read_b128 v[180:183], v166 offset:23136
	s_waitcnt lgkmcnt(1)
	v_mfma_f32_32x32x16_bf16 v[144:159], v[168:171], v[176:179], v[144:159]
	s_waitcnt lgkmcnt(0)
	v_mfma_f32_32x32x16_bf16 v[128:143], v[168:171], v[180:183], v[128:143]
	v_mfma_f32_32x32x16_bf16 v[112:127], v[172:175], v[176:179], v[112:127]
	v_mfma_f32_32x32x16_bf16 v[80:95], v[172:175], v[180:183], v[80:95]
	s_setprio 0
	s_add_i32 s21, s21, -1
	s_cmp_lg_u32 s21, 0
	s_cbranch_scc0 .LBB0_1315

;     ...
; #pragma unroll
;       for (int ks = 0; ks < 4; ++ks) {
;         bf16x8 af[2], bfr[2];
; #pragma unroll
;         for (int i = 0; i < 2; ++i) {
;           af[i] = *(const bf16x8*)(sA + (wm * 64 + i * 32) * LDT + fro + ks * 16);
;           bfr[i] = *(const bf16x8*)(sB + (wn * 64 + i * 32) * LDT + fro + ks * 16);
;         }
;         __builtin_amdgcn_s_setprio(1);
; #pragma unroll
;         for (int mi = 0; mi < 2; ++mi)
; #pragma unroll
;           for (int ni = 0; ni < 2; ++ni)
;             acc[mi][ni] = __builtin_amdgcn_mfma_f32_32x32x16_bf16(af[mi], bfr[ni], acc[mi][ni], 0, 0, 0);
;         __builtin_amdgcn_s_setprio(0);
;       }
.LBB0_1316:
	s_setprio 1
	ds_read_b128 v[234:237], v224
	ds_read_b128 v[250:253], v224 offset:4608
	ds_read_b128 v[244:247], v231 offset:18432
	ds_read_b128 v[238:241], v231 offset:23040
	s_waitcnt lgkmcnt(1)
	v_mfma_f32_32x32x16_bf16 v[176:191], v[234:237], v[244:247], v[176:191]
	s_waitcnt lgkmcnt(0)
	v_mfma_f32_32x32x16_bf16 v[160:175], v[234:237], v[238:241], v[160:175]
	v_mfma_f32_32x32x16_bf16 v[96:111], v[250:253], v[244:247], v[96:111]
	v_mfma_f32_32x32x16_bf16 v[64:79], v[250:253], v[238:241], v[64:79]
	ds_read_b128 v[234:237], v224 offset:32
	ds_read_b128 v[238:241], v224 offset:4640
	ds_read_b128 v[244:247], v231 offset:18464
	ds_read_b128 v[250:253], v231 offset:23072
	s_waitcnt lgkmcnt(1)
	v_mfma_f32_32x32x16_bf16 v[176:191], v[234:237], v[244:247], v[176:191]
	s_waitcnt lgkmcnt(0)
	v_mfma_f32_32x32x16_bf16 v[160:175], v[234:237], v[250:253], v[160:175]
	v_mfma_f32_32x32x16_bf16 v[96:111], v[238:241], v[244:247], v[96:111]
	v_mfma_f32_32x32x16_bf16 v[64:79], v[238:241], v[250:253], v[64:79]
	ds_read_b128 v[234:237], v224 offset:64
	ds_read_b128 v[238:241], v224 offset:4672
	ds_read_b128 v[244:247], v231 offset:18496
	ds_read_b128 v[250:253], v231 offset:23104
	s_waitcnt lgkmcnt(1)
	v_mfma_f32_32x32x16_bf16 v[176:191], v[234:237], v[244:247], v[176:191]
	s_waitcnt lgkmcnt(0)
	v_mfma_f32_32x32x16_bf16 v[160:175], v[234:237], v[250:253], v[160:175]
	v_mfma_f32_32x32x16_bf16 v[96:111], v[238:241], v[244:247], v[96:111]
	v_mfma_f32_32x32x16_bf16 v[64:79], v[238:241], v[250:253], v[64:79]
	ds_read_b128 v[234:237], v224 offset:96
	ds_read_b128 v[238:241], v224 offset:4704
	ds_read_b128 v[244:247], v231 offset:18528
	ds_read_b128 v[250:253], v231 offset:23136
	s_waitcnt lgkmcnt(1)
	v_mfma_f32_32x32x16_bf16 v[176:191], v[234:237], v[244:247], v[176:191]
	s_waitcnt lgkmcnt(0)
	v_mfma_f32_32x32x16_bf16 v[160:175], v[234:237], v[250:253], v[160:175]
	v_mfma_f32_32x32x16_bf16 v[96:111], v[238:241], v[244:247], v[96:111]
	v_mfma_f32_32x32x16_bf16 v[64:79], v[238:241], v[250:253], v[64:79]
	s_setprio 0
	s_add_i32 s20, s20, -1
	s_cmp_lg_u32 s20, 0
	s_cbranch_scc0 .LBB0_1304

; template <int MI>
; DEV void gemm_mm(f32x16 (&acc)[MI][2], const u16* __restrict__ A, int lda, const u16* __restrict__ B, int ldb, int K,
;                  unsigned char* smem) {
;     ...
;     bf16x8 af[2][MI], bfr[2][2];
; #pragma unroll
;     for (int i = 0; i < MI; ++i) af[0][i] = *(const bf16x8*)(sA + (wm * (MI * 32) + i * 32) * LDT + fro);
; #pragma unroll
;     for (int i = 0; i < 2; ++i) bfr[0][i] = *(const bf16x8*)(sB + (wn * 64 + i * 32) * LDT + fro);
; #pragma unroll
;     for (int ks = 0; ks < 4; ++ks) {
;       if (ks + 1 < 4) {
; #pragma unroll
;         for (int i = 0; i < MI; ++i)
;           af[(ks + 1) & 1][i] = *(const bf16x8*)(sA + (wm * (MI * 32) + i * 32) * LDT + fro + (ks + 1) * 16);
; #pragma unroll
;         for (int i = 0; i < 2; ++i)
;           bfr[(ks + 1) & 1][i] = *(const bf16x8*)(sB + (wn * 64 + i * 32) * LDT + fro + (ks + 1) * 16);
;       }
;       __builtin_amdgcn_sched_barrier(0);
;       __builtin_amdgcn_s_setprio(1);
; #pragma unroll
;       for (int mi = 0; mi < MI; ++mi)
; #pragma unroll
;         for (int ni = 0; ni < 2; ++ni)
;           acc[mi][ni] = __builtin_amdgcn_mfma_f32_32x32x16_bf16(af[ks & 1][mi], bfr[ks & 1][ni], acc[mi][ni], 0, 0, 0);
;       __builtin_amdgcn_s_setprio(0);
;       __builtin_amdgcn_sched_barrier(0);
;     }
.LBB0_1375:
	s_setprio 1
	ds_read_b128 v[184:187], v181
	ds_read_b128 v[188:191], v181 offset:32
	ds_read_b128 v[192:195], v181 offset:4608
	ds_read_b128 v[196:199], v181 offset:4640
	ds_read_b128 v[200:203], v181 offset:9216
	ds_read_b128 v[204:207], v181 offset:9248
	ds_read_b128 v[208:211], v181 offset:13824
	ds_read_b128 v[212:215], v181 offset:13856
	ds_read_b128 v[216:219], v182 offset:36864
	ds_read_b128 v[220:223], v182 offset:36896
	ds_read_b128 v[226:229], v182 offset:41472
	ds_read_b128 v[234:237], v182 offset:41504
	s_waitcnt lgkmcnt(3)
	v_mfma_f32_32x32x16_bf16 v[112:127], v[184:187], v[216:219], v[112:127]
	s_waitcnt lgkmcnt(1)
	v_mfma_f32_32x32x16_bf16 v[96:111], v[184:187], v[226:229], v[96:111]
	v_mfma_f32_32x32x16_bf16 v[80:95], v[192:195], v[216:219], v[80:95]
	v_mfma_f32_32x32x16_bf16 v[64:79], v[192:195], v[226:229], v[64:79]
	v_mfma_f32_32x32x16_bf16 v[48:63], v[200:203], v[216:219], v[48:63]
	v_mfma_f32_32x32x16_bf16 v[32:47], v[200:203], v[226:229], v[32:47]
	v_mfma_f32_32x32x16_bf16 v[16:31], v[208:211], v[216:219], v[16:31]
	v_mfma_f32_32x32x16_bf16 v[0:15], v[208:211], v[226:229], v[0:15]
	ds_read_b128 v[184:187], v181 offset:64
	ds_read_b128 v[192:195], v181 offset:4672
	ds_read_b128 v[200:203], v181 offset:9280
	ds_read_b128 v[208:211], v181 offset:13888
	ds_read_b128 v[216:219], v182 offset:36928
	ds_read_b128 v[226:229], v182 offset:41536
	v_mfma_f32_32x32x16_bf16 v[112:127], v[188:191], v[220:223], v[112:127]
	s_waitcnt lgkmcnt(6)
	v_mfma_f32_32x32x16_bf16 v[96:111], v[188:191], v[234:237], v[96:111]
	v_mfma_f32_32x32x16_bf16 v[80:95], v[196:199], v[220:223], v[80:95]
	v_mfma_f32_32x32x16_bf16 v[64:79], v[196:199], v[234:237], v[64:79]
	v_mfma_f32_32x32x16_bf16 v[48:63], v[204:207], v[220:223], v[48:63]
	v_mfma_f32_32x32x16_bf16 v[32:47], v[204:207], v[234:237], v[32:47]
	v_mfma_f32_32x32x16_bf16 v[16:31], v[212:215], v[220:223], v[16:31]
	v_mfma_f32_32x32x16_bf16 v[0:15], v[212:215], v[234:237], v[0:15]
	ds_read_b128 v[188:191], v181 offset:96
	ds_read_b128 v[196:199], v181 offset:4704
	ds_read_b128 v[204:207], v181 offset:9312
	ds_read_b128 v[212:215], v181 offset:13920
	ds_read_b128 v[220:223], v182 offset:36960
	ds_read_b128 v[234:237], v182 offset:41568
	s_waitcnt lgkmcnt(7)
	v_mfma_f32_32x32x16_bf16 v[112:127], v[184:187], v[216:219], v[112:127]
	s_waitcnt lgkmcnt(6)
	v_mfma_f32_32x32x16_bf16 v[96:111], v[184:187], v[226:229], v[96:111]
	v_mfma_f32_32x32x16_bf16 v[80:95], v[192:195], v[216:219], v[80:95]
	v_mfma_f32_32x32x16_bf16 v[64:79], v[192:195], v[226:229], v[64:79]
	v_mfma_f32_32x32x16_bf16 v[48:63], v[200:203], v[216:219], v[48:63]
	v_mfma_f32_32x32x16_bf16 v[32:47], v[200:203], v[226:229], v[32:47]
	v_mfma_f32_32x32x16_bf16 v[16:31], v[208:211], v[216:219], v[16:31]
	v_mfma_f32_32x32x16_bf16 v[0:15], v[208:211], v[226:229], v[0:15]
	s_waitcnt lgkmcnt(1)
	v_mfma_f32_32x32x16_bf16 v[112:127], v[188:191], v[220:223], v[112:127]
	s_waitcnt lgkmcnt(0)
	v_mfma_f32_32x32x16_bf16 v[96:111], v[188:191], v[234:237], v[96:111]
	v_mfma_f32_32x32x16_bf16 v[80:95], v[196:199], v[220:223], v[80:95]
	v_mfma_f32_32x32x16_bf16 v[64:79], v[196:199], v[234:237], v[64:79]
	v_mfma_f32_32x32x16_bf16 v[48:63], v[204:207], v[220:223], v[48:63]
	v_mfma_f32_32x32x16_bf16 v[32:47], v[204:207], v[234:237], v[32:47]
	v_mfma_f32_32x32x16_bf16 v[16:31], v[212:215], v[220:223], v[16:31]
	v_mfma_f32_32x32x16_bf16 v[0:15], v[212:215], v[234:237], v[0:15]
	s_setprio 0
	s_add_i32 s14, s14, -1
	s_cmp_lg_u32 s14, 0
	s_cbranch_scc0 .LBB0_1373

; template <int MI>
; DEV void gemm_mm(f32x16 (&acc)[MI][2], const u16* __restrict__ A, int lda, const u16* __restrict__ B, int ldb, int K,
;                  unsigned char* smem) {
;     ...
;     bf16x8 af[2][MI], bfr[2][2];
; #pragma unroll
;     for (int i = 0; i < MI; ++i) af[0][i] = *(const bf16x8*)(sA + (wm * (MI * 32) + i * 32) * LDT + fro);
; #pragma unroll
;     for (int i = 0; i < 2; ++i) bfr[0][i] = *(const bf16x8*)(sB + (wn * 64 + i * 32) * LDT + fro);
; #pragma unroll
;     for (int ks = 0; ks < 4; ++ks) {
;       if (ks + 1 < 4) {
; #pragma unroll
;         for (int i = 0; i < MI; ++i)
;           af[(ks + 1) & 1][i] = *(const bf16x8*)(sA + (wm * (MI * 32) + i * 32) * LDT + fro + (ks + 1) * 16);
; #pragma unroll
;         for (int i = 0; i < 2; ++i)
;           bfr[(ks + 1) & 1][i] = *(const bf16x8*)(sB + (wn * 64 + i * 32) * LDT + fro + (ks + 1) * 16);
;       }
;       __builtin_amdgcn_sched_barrier(0);
;       __builtin_amdgcn_s_setprio(1);
; #pragma unroll
;       for (int mi = 0; mi < MI; ++mi)
; #pragma unroll
;         for (int ni = 0; ni < 2; ++ni)
;           acc[mi][ni] = __builtin_amdgcn_mfma_f32_32x32x16_bf16(af[ks & 1][mi], bfr[ks & 1][ni], acc[mi][ni], 0, 0, 0);
;       __builtin_amdgcn_s_setprio(0);
;       __builtin_amdgcn_sched_barrier(0);
;     }
.LBB0_1382:
	s_setprio 1
	ds_read_b128 v[104:107], v101
	ds_read_b128 v[108:111], v101 offset:32
	ds_read_b128 v[112:115], v101 offset:4608
	ds_read_b128 v[116:119], v101 offset:4640
	ds_read_b128 v[120:123], v102 offset:18432
	ds_read_b128 v[124:127], v102 offset:18464
	ds_read_b128 v[128:131], v102 offset:23040
	ds_read_b128 v[132:135], v102 offset:23072
	s_add_i32 s12, s12, 1
	s_waitcnt lgkmcnt(3)
	v_mfma_f32_32x32x16_bf16 v[48:63], v[104:107], v[120:123], v[48:63]
	s_waitcnt lgkmcnt(1)
	v_mfma_f32_32x32x16_bf16 v[32:47], v[104:107], v[128:131], v[32:47]
	v_mfma_f32_32x32x16_bf16 v[16:31], v[112:115], v[120:123], v[16:31]
	v_mfma_f32_32x32x16_bf16 v[0:15], v[112:115], v[128:131], v[0:15]
	ds_read_b128 v[104:107], v101 offset:64
	ds_read_b128 v[112:115], v101 offset:4672
	ds_read_b128 v[120:123], v102 offset:18496
	ds_read_b128 v[128:131], v102 offset:23104
	v_mfma_f32_32x32x16_bf16 v[48:63], v[108:111], v[124:127], v[48:63]
	s_waitcnt lgkmcnt(4)
	v_mfma_f32_32x32x16_bf16 v[32:47], v[108:111], v[132:135], v[32:47]
	v_mfma_f32_32x32x16_bf16 v[16:31], v[116:119], v[124:127], v[16:31]
	v_mfma_f32_32x32x16_bf16 v[0:15], v[116:119], v[132:135], v[0:15]
	ds_read_b128 v[108:111], v101 offset:96
	ds_read_b128 v[116:119], v101 offset:4704
	ds_read_b128 v[124:127], v102 offset:18528
	ds_read_b128 v[132:135], v102 offset:23136
	s_waitcnt lgkmcnt(5)
	v_mfma_f32_32x32x16_bf16 v[48:63], v[104:107], v[120:123], v[48:63]
	s_waitcnt lgkmcnt(4)
	v_mfma_f32_32x32x16_bf16 v[32:47], v[104:107], v[128:131], v[32:47]
	v_mfma_f32_32x32x16_bf16 v[16:31], v[112:115], v[120:123], v[16:31]
	v_mfma_f32_32x32x16_bf16 v[0:15], v[112:115], v[128:131], v[0:15]
	s_waitcnt lgkmcnt(1)
	v_mfma_f32_32x32x16_bf16 v[48:63], v[108:111], v[124:127], v[48:63]
	s_waitcnt lgkmcnt(0)
	v_mfma_f32_32x32x16_bf16 v[32:47], v[108:111], v[132:135], v[32:47]
	v_mfma_f32_32x32x16_bf16 v[16:31], v[116:119], v[124:127], v[16:31]
	v_mfma_f32_32x32x16_bf16 v[0:15], v[116:119], v[132:135], v[0:15]
	s_setprio 0
	s_cmp_lg_u32 s12, 16
	s_cbranch_scc0 .LBB0_1380
